# v25 + one static s_setprio 1 for waves 4-7 around the GEMM K-loop (reset at exit)
# baseline (speedup 1.0000x reference)
.LBB0_247:
	v_readlane_b32 s3, v255, 19
	v_mov_b32_e32 v2, 0
	s_add_i32 s2, s10, s1
	s_add_i32 s3, s3, s1
	s_add_i32 s14, s16, s1
	s_movk_i32 s15, 0x100
	s_mov_b32 s28, 2
	v_mov_b32_e32 v3, v2
	v_mov_b32_e32 v4, v2
	v_mov_b32_e32 v5, v2
	v_mov_b32_e32 v6, v2
	v_mov_b32_e32 v7, v2
	v_mov_b32_e32 v8, v2
	v_mov_b32_e32 v9, v2
	v_mov_b32_e32 v10, v2
	v_mov_b32_e32 v11, v2
	v_mov_b32_e32 v12, v2
	v_mov_b32_e32 v13, v2
	v_mov_b32_e32 v14, v2
	v_mov_b32_e32 v15, v2
	v_mov_b32_e32 v16, v2
	v_mov_b32_e32 v17, v2
	v_mov_b32_e32 v18, v2
	v_mov_b32_e32 v19, v2
	v_mov_b32_e32 v20, v2
	v_mov_b32_e32 v21, v2
	v_mov_b32_e32 v22, v2
	v_mov_b32_e32 v23, v2
	v_mov_b32_e32 v24, v2
	v_mov_b32_e32 v25, v2
	v_mov_b32_e32 v26, v2
	v_mov_b32_e32 v27, v2
	v_mov_b32_e32 v28, v2
	v_mov_b32_e32 v29, v2
	v_mov_b32_e32 v30, v2
	v_mov_b32_e32 v31, v2
	v_mov_b32_e32 v32, v2
	v_mov_b32_e32 v33, v2
	v_mov_b32_e32 v34, v2
	v_mov_b32_e32 v35, v2
	v_mov_b32_e32 v36, v2
	v_mov_b32_e32 v37, v2
	v_mov_b32_e32 v38, v2
	v_mov_b32_e32 v39, v2
	v_mov_b32_e32 v40, v2
	v_mov_b32_e32 v41, v2
	v_mov_b32_e32 v42, v2
	v_mov_b32_e32 v43, v2
	v_mov_b32_e32 v44, v2
	v_mov_b32_e32 v45, v2
	v_mov_b32_e32 v46, v2
	v_mov_b32_e32 v47, v2
	v_mov_b32_e32 v48, v2
	v_mov_b32_e32 v49, v2
	v_mov_b32_e32 v50, v2
	v_mov_b32_e32 v51, v2
	v_mov_b32_e32 v52, v2
	v_mov_b32_e32 v53, v2
	v_mov_b32_e32 v54, v2
	v_mov_b32_e32 v55, v2
	v_mov_b32_e32 v56, v2
	v_mov_b32_e32 v57, v2
	v_mov_b32_e32 v58, v2
	v_mov_b32_e32 v59, v2
	v_mov_b32_e32 v60, v2
	v_mov_b32_e32 v61, v2
	v_mov_b32_e32 v62, v2
	v_mov_b32_e32 v63, v2
	v_mov_b32_e32 v64, v2
	v_mov_b32_e32 v65, v2
	v_mov_b32_e32 v66, v2
	v_mov_b32_e32 v67, v2
	v_mov_b32_e32 v68, v2
	v_mov_b32_e32 v69, v2
	v_mov_b32_e32 v70, v2
	v_mov_b32_e32 v71, v2
	v_mov_b32_e32 v72, v2
	v_mov_b32_e32 v73, v2
	v_mov_b32_e32 v74, v2
	v_mov_b32_e32 v75, v2
	v_mov_b32_e32 v76, v2
	v_mov_b32_e32 v77, v2
	v_mov_b32_e32 v78, v2
	v_mov_b32_e32 v79, v2
	v_mov_b32_e32 v80, v2
	v_mov_b32_e32 v81, v2
	v_mov_b32_e32 v82, v2
	v_mov_b32_e32 v83, v2
	v_mov_b32_e32 v84, v2
	v_mov_b32_e32 v85, v2
	v_mov_b32_e32 v86, v2
	v_mov_b32_e32 v87, v2
	v_mov_b32_e32 v88, v2
	v_mov_b32_e32 v89, v2
	v_mov_b32_e32 v90, v2
	v_mov_b32_e32 v91, v2
	v_mov_b32_e32 v92, v2
	v_mov_b32_e32 v93, v2
	v_mov_b32_e32 v94, v2
	v_mov_b32_e32 v95, v2
	v_mov_b32_e32 v96, v2
	v_mov_b32_e32 v97, v2
	v_mov_b32_e32 v98, v2
	v_mov_b32_e32 v99, v2
	v_mov_b32_e32 v100, v2
	v_mov_b32_e32 v101, v2
	v_mov_b32_e32 v102, v2
	v_mov_b32_e32 v103, v2
	v_mov_b32_e32 v104, v2
	v_mov_b32_e32 v105, v2
	v_mov_b32_e32 v106, v2
	v_mov_b32_e32 v107, v2
	v_mov_b32_e32 v108, v2
	v_mov_b32_e32 v109, v2
	v_mov_b32_e32 v110, v2
	v_mov_b32_e32 v111, v2
	v_mov_b32_e32 v112, v2
	v_mov_b32_e32 v113, v2
	v_mov_b32_e32 v114, v2
	v_mov_b32_e32 v115, v2
	v_mov_b32_e32 v116, v2
	v_mov_b32_e32 v117, v2
	v_mov_b32_e32 v118, v2
	v_mov_b32_e32 v119, v2
	v_mov_b32_e32 v120, v2
	v_mov_b32_e32 v121, v2
	v_mov_b32_e32 v122, v2
	v_mov_b32_e32 v123, v2
	v_mov_b32_e32 v124, v2
	v_mov_b32_e32 v125, v2
	v_mov_b32_e32 v126, v2
	v_mov_b32_e32 v127, v2
	v_mov_b32_e32 v128, v2
	v_mov_b32_e32 v129, v2
	v_add_u32_e32 v235, 0x10000, v231
	v_add_u32_e32 v237, 0x10000, v233
	v_add_u32_e32 v226, 0x10000, v239
	v_add_u32_e32 v228, 0x10000, v241
	ds_read_b128 v[130:133], v239 offset:32768
	ds_read_b128 v[134:137], v239 offset:34816
	ds_read_b128 v[138:141], v239 offset:36864
	ds_read_b128 v[142:145], v239 offset:38912
	ds_read_b128 v[146:149], v231
	ds_read_b128 v[150:153], v231 offset:2048
	ds_read_b128 v[154:157], v231 offset:4096
	ds_read_b128 v[158:161], v231 offset:6144
	ds_read_b128 v[162:165], v231 offset:8192
	ds_read_b128 v[166:169], v231 offset:10240
	ds_read_b128 v[170:173], v231 offset:12288
	ds_read_b128 v[174:177], v231 offset:14336
	s_add_i32 s38, s15, 0xffffff80
	s_mov_b32 m0, s9
	s_add_i32 s39, s96, s38
	buffer_load_dwordx4 v227, s[40:43], s39 offen lds
	s_mov_b32 m0, s72
	s_add_i32 s39, s1, s38
	buffer_load_dwordx4 v227, s[60:63], s39 offen lds
	s_mov_b32 m0, s13
	s_add_i32 s39, s12, s38
	buffer_load_dwordx4 v229, s[40:43], s39 offen lds
	s_mov_b32 m0, s85
	s_add_i32 s39, s14, s38
	buffer_load_dwordx4 v229, s[60:63], s39 offen lds
	s_mov_b32 m0, s11
	s_add_i32 s39, s86, s38
	buffer_load_dwordx4 v227, s[40:43], s39 offen lds
	s_mov_b32 m0, s84
	s_add_i32 s39, s2, s38
	buffer_load_dwordx4 v227, s[60:63], s39 offen lds
	s_mov_b32 m0, s8
	s_add_i32 s39, s21, s38
	buffer_load_dwordx4 v229, s[40:43], s39 offen lds
	s_mov_b32 m0, s34
	s_add_i32 s39, s3, s38
	buffer_load_dwordx4 v229, s[60:63], s39 offen lds
	s_waitcnt lgkmcnt(0)
	s_bitcmp1_b32 s76, 14
	s_cbranch_scc0 .Lgk_noprio
	s_setprio 1

.Lgk_even_mid:
	s_cmp_lt_u32 s28, s47
	s_cselect_b64 s[30:31], -1, 0
	s_cmp_ge_u32 s28, s47
	s_cselect_b64 s[6:7], -1, 0
	s_or_b64 s[36:37], s[26:27], s[30:31]
	s_and_b64 s[30:31], s[30:31], exec
	s_cselect_b32 s30, s1, s5
	s_cselect_b32 s29, s15, 0
	s_cselect_b32 s67, s43, s93
	s_cselect_b32 s66, s42, s92
	s_cselect_b32 s65, s41, s57
	s_cselect_b32 s64, s40, s56
	s_cselect_b32 s71, s63, s91
	s_cselect_b32 s70, s62, s90
	s_cselect_b32 s69, s61, s53
	s_cselect_b32 s68, s60, s52
	s_add_i32 s30, s29, s30
	s_and_b32 s66, s66, s36
	s_and_b32 s70, s70, s36
	v_mfma_f32_16x16x32_bf16 v[126:129], v[130:133], v[146:149], v[126:129]
	ds_read_b128 v[178:181], v241 offset:32768
	v_mfma_f32_16x16x32_bf16 v[122:125], v[134:137], v[146:149], v[122:125]
	v_mfma_f32_16x16x32_bf16 v[118:121], v[138:141], v[146:149], v[118:121]
	ds_read_b128 v[182:185], v241 offset:34816
	v_mfma_f32_16x16x32_bf16 v[114:117], v[142:145], v[146:149], v[114:117]
	v_mfma_f32_16x16x32_bf16 v[110:113], v[130:133], v[150:153], v[110:113]
	ds_read_b128 v[186:189], v241 offset:36864
	v_mfma_f32_16x16x32_bf16 v[106:109], v[134:137], v[150:153], v[106:109]
	v_mfma_f32_16x16x32_bf16 v[102:105], v[138:141], v[150:153], v[102:105]
	ds_read_b128 v[190:193], v241 offset:38912
	v_mfma_f32_16x16x32_bf16 v[98:101], v[142:145], v[150:153], v[98:101]
	v_mfma_f32_16x16x32_bf16 v[94:97], v[130:133], v[154:157], v[94:97]
	ds_read_b128 v[194:197], v233
	v_mfma_f32_16x16x32_bf16 v[90:93], v[134:137], v[154:157], v[90:93]
	v_mfma_f32_16x16x32_bf16 v[86:89], v[138:141], v[154:157], v[86:89]
	ds_read_b128 v[198:201], v233 offset:2048
	v_mfma_f32_16x16x32_bf16 v[82:85], v[142:145], v[154:157], v[82:85]
	v_mfma_f32_16x16x32_bf16 v[78:81], v[130:133], v[158:161], v[78:81]
	ds_read_b128 v[202:205], v233 offset:4096
	v_mfma_f32_16x16x32_bf16 v[74:77], v[134:137], v[158:161], v[74:77]
	v_mfma_f32_16x16x32_bf16 v[70:73], v[138:141], v[158:161], v[70:73]
	ds_read_b128 v[206:209], v233 offset:6144
	v_mfma_f32_16x16x32_bf16 v[66:69], v[142:145], v[158:161], v[66:69]
	v_mfma_f32_16x16x32_bf16 v[62:65], v[130:133], v[162:165], v[62:65]
	ds_read_b128 v[210:213], v233 offset:8192
	v_mfma_f32_16x16x32_bf16 v[58:61], v[134:137], v[162:165], v[58:61]
	v_mfma_f32_16x16x32_bf16 v[54:57], v[138:141], v[162:165], v[54:57]
	ds_read_b128 v[214:217], v233 offset:10240
	v_mfma_f32_16x16x32_bf16 v[50:53], v[142:145], v[162:165], v[50:53]
	v_mfma_f32_16x16x32_bf16 v[46:49], v[130:133], v[166:169], v[46:49]
	ds_read_b128 v[218:221], v233 offset:12288
	v_mfma_f32_16x16x32_bf16 v[42:45], v[134:137], v[166:169], v[42:45]
	v_mfma_f32_16x16x32_bf16 v[38:41], v[138:141], v[166:169], v[38:41]
	ds_read_b128 v[222:225], v233 offset:14336
	v_mfma_f32_16x16x32_bf16 v[34:37], v[142:145], v[166:169], v[34:37]
	v_mfma_f32_16x16x32_bf16 v[30:33], v[130:133], v[170:173], v[30:33]
	v_mfma_f32_16x16x32_bf16 v[26:29], v[134:137], v[170:173], v[26:29]
	v_mfma_f32_16x16x32_bf16 v[22:25], v[138:141], v[170:173], v[22:25]
	v_mfma_f32_16x16x32_bf16 v[18:21], v[142:145], v[170:173], v[18:21]
	v_mfma_f32_16x16x32_bf16 v[14:17], v[130:133], v[174:177], v[14:17]
	v_mfma_f32_16x16x32_bf16 v[10:13], v[134:137], v[174:177], v[10:13]
	v_mfma_f32_16x16x32_bf16 v[6:9], v[138:141], v[174:177], v[6:9]
	v_mfma_f32_16x16x32_bf16 v[2:5], v[142:145], v[174:177], v[2:5]
	s_waitcnt vmcnt(0) lgkmcnt(0)
	s_barrier
	v_mfma_f32_16x16x32_bf16 v[126:129], v[178:181], v[194:197], v[126:129]
	ds_read_b128 v[130:133], v226 offset:32768
	v_mfma_f32_16x16x32_bf16 v[122:125], v[182:185], v[194:197], v[122:125]
	s_mov_b32 m0, s76
	s_add_i32 s39, s29, s96
	buffer_load_dwordx4 v227, s[64:67], s39 offen lds
	v_mfma_f32_16x16x32_bf16 v[118:121], v[186:189], v[194:197], v[118:121]
	ds_read_b128 v[134:137], v226 offset:34816
	v_mfma_f32_16x16x32_bf16 v[114:117], v[190:193], v[194:197], v[114:117]
	v_mfma_f32_16x16x32_bf16 v[110:113], v[178:181], v[198:201], v[110:113]
	ds_read_b128 v[138:141], v226 offset:36864
	v_mfma_f32_16x16x32_bf16 v[106:109], v[182:185], v[198:201], v[106:109]
	s_mov_b32 m0, s97
	s_nop 0
	buffer_load_dwordx4 v227, s[68:71], s30 offen lds
	v_mfma_f32_16x16x32_bf16 v[102:105], v[186:189], v[198:201], v[102:105]
	ds_read_b128 v[142:145], v226 offset:38912
	v_mfma_f32_16x16x32_bf16 v[98:101], v[190:193], v[198:201], v[98:101]
	v_mfma_f32_16x16x32_bf16 v[94:97], v[178:181], v[202:205], v[94:97]
	ds_read_b128 v[146:149], v235
	v_mfma_f32_16x16x32_bf16 v[90:93], v[182:185], v[202:205], v[90:93]
	s_mov_b32 m0, s94
	s_add_i32 s39, s29, s12
	buffer_load_dwordx4 v229, s[64:67], s39 offen lds
	v_mfma_f32_16x16x32_bf16 v[86:89], v[186:189], v[202:205], v[86:89]
	ds_read_b128 v[150:153], v235 offset:2048
	v_mfma_f32_16x16x32_bf16 v[82:85], v[190:193], v[202:205], v[82:85]
	v_mfma_f32_16x16x32_bf16 v[78:81], v[178:181], v[206:209], v[78:81]
	ds_read_b128 v[154:157], v235 offset:4096
	v_mfma_f32_16x16x32_bf16 v[74:77], v[182:185], v[206:209], v[74:77]
	s_mov_b32 m0, s95
	s_add_i32 s39, s30, s16
	buffer_load_dwordx4 v229, s[68:71], s39 offen lds
	v_mfma_f32_16x16x32_bf16 v[70:73], v[186:189], v[206:209], v[70:73]
	ds_read_b128 v[158:161], v235 offset:6144
	v_mfma_f32_16x16x32_bf16 v[66:69], v[190:193], v[206:209], v[66:69]
	v_mfma_f32_16x16x32_bf16 v[62:65], v[178:181], v[210:213], v[62:65]
	ds_read_b128 v[162:165], v235 offset:8192
	v_mfma_f32_16x16x32_bf16 v[58:61], v[182:185], v[210:213], v[58:61]
	s_mov_b32 m0, s87
	s_add_i32 s39, s29, s86
	buffer_load_dwordx4 v227, s[64:67], s39 offen lds
	v_mfma_f32_16x16x32_bf16 v[54:57], v[186:189], v[210:213], v[54:57]
	ds_read_b128 v[166:169], v235 offset:10240
	v_mfma_f32_16x16x32_bf16 v[50:53], v[190:193], v[210:213], v[50:53]
	v_mfma_f32_16x16x32_bf16 v[46:49], v[178:181], v[214:217], v[46:49]
	ds_read_b128 v[170:173], v235 offset:12288
	v_mfma_f32_16x16x32_bf16 v[42:45], v[182:185], v[214:217], v[42:45]
	s_mov_b32 m0, s20
	s_add_i32 s39, s30, s10
	buffer_load_dwordx4 v227, s[68:71], s39 offen lds
	v_mfma_f32_16x16x32_bf16 v[38:41], v[186:189], v[214:217], v[38:41]
	ds_read_b128 v[174:177], v235 offset:14336
	v_mfma_f32_16x16x32_bf16 v[34:37], v[190:193], v[214:217], v[34:37]
	v_mfma_f32_16x16x32_bf16 v[30:33], v[178:181], v[218:221], v[30:33]
	v_mfma_f32_16x16x32_bf16 v[26:29], v[182:185], v[218:221], v[26:29]
	s_mov_b32 m0, s22
	s_add_i32 s39, s29, s21
	buffer_load_dwordx4 v229, s[64:67], s39 offen lds
	v_mfma_f32_16x16x32_bf16 v[22:25], v[186:189], v[218:221], v[22:25]
	v_mfma_f32_16x16x32_bf16 v[18:21], v[190:193], v[218:221], v[18:21]
	v_mfma_f32_16x16x32_bf16 v[14:17], v[178:181], v[222:225], v[14:17]
	v_mfma_f32_16x16x32_bf16 v[10:13], v[182:185], v[222:225], v[10:13]
	s_mov_b32 m0, s23
	s_add_i32 s37, s30, s10
	s_add_i32 s39, s37, s16
	buffer_load_dwordx4 v229, s[68:71], s39 offen lds
	v_mfma_f32_16x16x32_bf16 v[6:9], v[186:189], v[222:225], v[6:9]
	v_mfma_f32_16x16x32_bf16 v[2:5], v[190:193], v[222:225], v[2:5]
	s_waitcnt lgkmcnt(0)
	v_mfma_f32_16x16x32_bf16 v[126:129], v[130:133], v[146:149], v[126:129]
	ds_read_b128 v[178:181], v228 offset:32768
	v_mfma_f32_16x16x32_bf16 v[122:125], v[134:137], v[146:149], v[122:125]
	v_mfma_f32_16x16x32_bf16 v[118:121], v[138:141], v[146:149], v[118:121]
	ds_read_b128 v[182:185], v228 offset:34816
	v_mfma_f32_16x16x32_bf16 v[114:117], v[142:145], v[146:149], v[114:117]
	v_mfma_f32_16x16x32_bf16 v[110:113], v[130:133], v[150:153], v[110:113]
	ds_read_b128 v[186:189], v228 offset:36864
	v_mfma_f32_16x16x32_bf16 v[106:109], v[134:137], v[150:153], v[106:109]
	v_mfma_f32_16x16x32_bf16 v[102:105], v[138:141], v[150:153], v[102:105]
	ds_read_b128 v[190:193], v228 offset:38912
	v_mfma_f32_16x16x32_bf16 v[98:101], v[142:145], v[150:153], v[98:101]
	v_mfma_f32_16x16x32_bf16 v[94:97], v[130:133], v[154:157], v[94:97]
	ds_read_b128 v[194:197], v237
	v_mfma_f32_16x16x32_bf16 v[90:93], v[134:137], v[154:157], v[90:93]
	v_mfma_f32_16x16x32_bf16 v[86:89], v[138:141], v[154:157], v[86:89]
	ds_read_b128 v[198:201], v237 offset:2048
	v_mfma_f32_16x16x32_bf16 v[82:85], v[142:145], v[154:157], v[82:85]
	v_mfma_f32_16x16x32_bf16 v[78:81], v[130:133], v[158:161], v[78:81]
	ds_read_b128 v[202:205], v237 offset:4096
	v_mfma_f32_16x16x32_bf16 v[74:77], v[134:137], v[158:161], v[74:77]
	v_mfma_f32_16x16x32_bf16 v[70:73], v[138:141], v[158:161], v[70:73]
	ds_read_b128 v[206:209], v237 offset:6144
	v_mfma_f32_16x16x32_bf16 v[66:69], v[142:145], v[158:161], v[66:69]
	v_mfma_f32_16x16x32_bf16 v[62:65], v[130:133], v[162:165], v[62:65]
	ds_read_b128 v[210:213], v237 offset:8192
	v_mfma_f32_16x16x32_bf16 v[58:61], v[134:137], v[162:165], v[58:61]
	v_mfma_f32_16x16x32_bf16 v[54:57], v[138:141], v[162:165], v[54:57]
	ds_read_b128 v[214:217], v237 offset:10240
	v_mfma_f32_16x16x32_bf16 v[50:53], v[142:145], v[162:165], v[50:53]
	v_mfma_f32_16x16x32_bf16 v[46:49], v[130:133], v[166:169], v[46:49]
	ds_read_b128 v[218:221], v237 offset:12288
	v_mfma_f32_16x16x32_bf16 v[42:45], v[134:137], v[166:169], v[42:45]
	v_mfma_f32_16x16x32_bf16 v[38:41], v[138:141], v[166:169], v[38:41]
	ds_read_b128 v[222:225], v237 offset:14336
	v_mfma_f32_16x16x32_bf16 v[34:37], v[142:145], v[166:169], v[34:37]
	v_mfma_f32_16x16x32_bf16 v[30:33], v[130:133], v[170:173], v[30:33]
	v_mfma_f32_16x16x32_bf16 v[26:29], v[134:137], v[170:173], v[26:29]
	v_mfma_f32_16x16x32_bf16 v[22:25], v[138:141], v[170:173], v[22:25]
	v_mfma_f32_16x16x32_bf16 v[18:21], v[142:145], v[170:173], v[18:21]
	v_mfma_f32_16x16x32_bf16 v[14:17], v[130:133], v[174:177], v[14:17]
	v_mfma_f32_16x16x32_bf16 v[10:13], v[134:137], v[174:177], v[10:13]
	v_mfma_f32_16x16x32_bf16 v[6:9], v[138:141], v[174:177], v[6:9]
	v_mfma_f32_16x16x32_bf16 v[2:5], v[142:145], v[174:177], v[2:5]
	s_addk_i32 s15, 0x100
	s_add_i32 s28, s28, 2
	s_and_b64 vcc, exec, s[6:7]
	s_waitcnt vmcnt(0) lgkmcnt(0)
	s_barrier
	s_cbranch_vccz .Lgk_even_top
	s_setprio 0
	v_mov_b32_e32 v226, 0x8000
	v_mov_b32_e32 v228, 0x8004
